# diff steady body variant: softmax of tile i interleaved with the PV MFMAs of tile i-1 in the same wave (all waves same role), with the same per-unit prologue/epilogue de-serialisations
# baseline (speedup 1.0000x reference)
; __device__ __forceinline__ s16x4 vtr(ldsp p) { return __builtin_bit_cast(s16x4, __builtin_amdgcn_ds_read_tr16_b64_v4i16((LAS v4i16_t*)p)); }
; template <bool DIFF>
; __device__ __forceinline__ void attn_unit(const AttnP& A, int b, int h, int qi, ldsp lds) {
;     ...
;     for (int kt = kt0; kt < nt; ++kt) {
;         if (kt + 1 < nt) LOAD_TILE(kt + 1);
;         if (64 * kt <= qmax_w) {
;             ldsp Kb = lds + (kt & 1) * STAGE; ldsp Vb = Kb + 64 * KP;
;             bf16x8 kf[8]; bf16x8 ka0, ka1, qa; f32x16 s0, s1;
;     ...
;             QK_BLOCK();
;             s16x4 vlo[8], vhi[8];
; #pragma unroll
;             for (int t = 0; t < 2; ++t)
; #pragma unroll
;                 for (int j = 0; j < 4; ++j) { vlo[t * 4 + j] = vtr(Vb + trb + (16 * j) * VP + t * 64); vhi[t * 4 + j] = vtr(Vb + trb + (16 * j + 8) * VP + t * 64); }
;             __builtin_amdgcn_sched_barrier(0);
;             MASK_BLOCK();
;             bool full = (kt == kt0);
;             float psa, psb;
;             if (!full) {
;                 EXPSUM_BLOCK();
;     ...
;             for (int t = 0; t < 2; ++t)
; #pragma unroll
;                 for (int j = 0; j < 4; ++j) {
;                     const bf16x8 vf = (bf16x8){vlo[t * 4 + j][0], vlo[t * 4 + j][1], vlo[t * 4 + j][2], vlo[t * 4 + j][3], vhi[t * 4 + j][0], vhi[t * 4 + j][1], vhi[t * 4 + j][2], vhi[t * 4 + j][3]};
;                     o[t] = __builtin_amdgcn_mfma_f32_32x32x16_bf16(vf, pw[j], o[t], 0, 0, 0);
;                 }
;             if (DIFF) {
; #pragma unroll
;                 for (int t = 2; t < NTD; ++t)
; #pragma unroll
;                     for (int j = 0; j < 4; ++j) { vlo[(t - 2) * 4 + j] = vtr(Vb + trb + (16 * j) * VP + t * 64); vhi[(t - 2) * 4 + j] = vtr(Vb + trb + (16 * j + 8) * VP + t * 64); }
;                 __builtin_amdgcn_sched_barrier(0);
; #pragma unroll
;                 for (int t = 2; t < NTD; ++t)
; #pragma unroll
;                     for (int j = 0; j < 4; ++j) {
;                         const int i = (t - 2) * 4 + j;
;                         const bf16x8 vf = (bf16x8){vlo[i][0], vlo[i][1], vlo[i][2], vlo[i][3], vhi[i][0], vhi[i][1], vhi[i][2], vhi[i][3]};
;                         o[t] = __builtin_amdgcn_mfma_f32_32x32x16_bf16(vf, pw[j], o[t], 0, 0, 0);
;                     }
.Lda_top:
	s_and_b64 vcc, exec, s[16:17]
	s_cbranch_vccz .Lda_gen
	s_cmp_lt_i32 s75, 1
	s_cbranch_scc1 .Lda_gen
	s_add_i32 s23, s31, -3
	s_cmp_gt_i32 s75, s23
	s_cbranch_scc1 .Lda_gen
.Ldc_entry:
	v_mov_b32_e32 v148, v98
	v_mov_b32_e32 v149, v99
	v_mov_b32_e32 v150, v100
	v_mov_b32_e32 v151, v101
	v_mov_b32_e32 v152, v102
	v_mov_b32_e32 v153, v103
	v_mov_b32_e32 v154, v104
	v_mov_b32_e32 v155, v105
	v_mov_b32_e32 v156, v82
	v_mov_b32_e32 v157, v83
	v_mov_b32_e32 v158, v84
	v_mov_b32_e32 v159, v85
	v_mov_b32_e32 v160, v86
	v_mov_b32_e32 v161, v87
	v_mov_b32_e32 v162, v88
	v_mov_b32_e32 v163, v89
	s_bitcmp1_b32 s75, 0
	s_cbranch_scc1 .Ldc_odd_in
.Ldc_even_in:
	ds_read_b128 v[164:167], v234
	ds_read_b128 v[168:171], v234 offset:32
	ds_read_b128 v[172:175], v234 offset:64
	ds_read_b128 v[176:179], v234 offset:96
	ds_read_b128 v[240:243], v234 offset:8704
	ds_read_b128 v[244:247], v234 offset:8736
	s_branch .Ldc_even_mid
.Ldc_odd_in:
	ds_read_b128 v[164:167], v234 offset:38144
	ds_read_b128 v[168:171], v234 offset:38176
	ds_read_b128 v[172:175], v234 offset:38208
	ds_read_b128 v[176:179], v234 offset:38240
	ds_read_b128 v[240:243], v234 offset:46848
	ds_read_b128 v[244:247], v234 offset:46880
	s_branch .Ldc_odd_mid
.Ldc_even:
	ds_read_b128 v[164:167], v234
	ds_read_b128 v[168:171], v234 offset:32
	ds_read_b128 v[172:175], v234 offset:64
	ds_read_b128 v[176:179], v234 offset:96
	ds_read_b128 v[240:243], v234 offset:8704
	ds_read_b128 v[244:247], v234 offset:8736
	v_cvt_pk_bf16_f32 v148, v98, v99
	v_cvt_pk_bf16_f32 v149, v100, v101
	v_cvt_pk_bf16_f32 v150, v102, v103
	v_cvt_pk_bf16_f32 v151, v104, v105
	v_cvt_pk_bf16_f32 v152, v106, v107
	v_cvt_pk_bf16_f32 v153, v108, v109
	v_cvt_pk_bf16_f32 v154, v110, v111
	v_cvt_pk_bf16_f32 v155, v112, v113
	v_cvt_pk_bf16_f32 v156, v82, v83
	v_cvt_pk_bf16_f32 v157, v84, v85
	v_cvt_pk_bf16_f32 v158, v86, v87
	v_cvt_pk_bf16_f32 v159, v88, v89
	v_cvt_pk_bf16_f32 v160, v90, v91
	v_cvt_pk_bf16_f32 v161, v92, v93
	v_cvt_pk_bf16_f32 v162, v94, v95
	v_cvt_pk_bf16_f32 v163, v96, v97
.Ldc_even_mid:
	s_waitcnt lgkmcnt(5)
	v_mfma_f32_32x32x16_bf16 v[98:113], v[164:167], v[116:119], v[66:81]
	ds_read_b128 v[248:251], v234 offset:8768
	s_waitcnt vmcnt(0)
	s_waitcnt lgkmcnt(5)
	v_mfma_f32_32x32x16_bf16 v[98:113], v[168:171], v[120:123], v[98:113]
	ds_read_b128 v[164:167], v234 offset:8800
	ds_write_b128 v226, v[132:135] offset:38144
	s_waitcnt lgkmcnt(6)
	v_mfma_f32_32x32x16_bf16 v[98:113], v[172:175], v[124:127], v[98:113]
	ds_read_b64_tr_b16 v[168:169], v252 offset:17472
	ds_read_b64_tr_b16 v[170:171], v252 offset:20032
	ds_write_b128 v228, v[140:143] offset:38144
	s_waitcnt lgkmcnt(8)
	v_mfma_f32_32x32x16_bf16 v[98:113], v[176:179], v[128:131], v[98:113]
	ds_read_b64_tr_b16 v[172:173], v252 offset:17408
	ds_read_b64_tr_b16 v[174:175], v252 offset:19968
	ds_write_b128 v227, v[136:139] offset:17408
	s_waitcnt lgkmcnt(10)
	v_mfma_f32_32x32x16_bf16 v[82:97], v[240:243], v[116:119], v[66:81]
	ds_read_b64_tr_b16 v[176:177], v252 offset:22592
	ds_read_b64_tr_b16 v[178:179], v252 offset:25152
	ds_write_b128 v229, v[144:147] offset:17408
	s_waitcnt lgkmcnt(12)
	v_mfma_f32_32x32x16_bf16 v[82:97], v[244:247], v[120:123], v[82:97]
	ds_read_b64_tr_b16 v[240:241], v252 offset:22528
	ds_read_b64_tr_b16 v[242:243], v252 offset:25088
	global_load_dwordx4 v[136:139], v[196:197], off offset:2048
	global_load_dwordx4 v[144:147], v[198:199], off offset:2048
	v_lshl_add_u64 v[196:197], v[196:197], 0, s[26:27]
	v_lshl_add_u64 v[198:199], v[198:199], 0, s[26:27]
	s_waitcnt lgkmcnt(13)
	v_mfma_f32_32x32x16_bf16 v[82:97], v[248:251], v[124:127], v[82:97]
	ds_read_b64_tr_b16 v[244:245], v252 offset:27712
	ds_read_b64_tr_b16 v[246:247], v252 offset:30272
	global_load_dwordx4 v[132:135], v[196:197], off offset:1024
	global_load_dwordx4 v[140:143], v[198:199], off offset:1024
	s_waitcnt lgkmcnt(14)
	v_mfma_f32_32x32x16_bf16 v[82:97], v[164:167], v[128:131], v[82:97]
	ds_read_b64_tr_b16 v[248:249], v252 offset:27648
	ds_read_b64_tr_b16 v[250:251], v252 offset:30208
	v_exp_f32_e32 v98, v98
	v_exp_f32_e32 v99, v99
	v_add_f32_e32 v237, 0, v98
	v_exp_f32_e32 v100, v100
	s_waitcnt lgkmcnt(13)
	v_mfma_f32_32x32x16_bf16 v[34:49], v[168:171], v[148:151], v[34:49]
	ds_read_b64_tr_b16 v[164:165], v252 offset:32768
	ds_read_b64_tr_b16 v[166:167], v252 offset:35328
	v_add_f32_e32 v237, v99, v237
	v_exp_f32_e32 v101, v101
	v_add_f32_e32 v237, v100, v237
	v_exp_f32_e32 v102, v102
	s_waitcnt lgkmcnt(12)
	v_mfma_f32_32x32x16_bf16 v[50:65], v[172:175], v[148:151], v[50:65]
	ds_read_b64_tr_b16 v[168:169], v252 offset:32832
	ds_read_b64_tr_b16 v[170:171], v252 offset:35392
	v_add_f32_e32 v237, v101, v237
	v_exp_f32_e32 v103, v103
	v_add_f32_e32 v237, v102, v237
	v_exp_f32_e32 v104, v104
	s_waitcnt lgkmcnt(11)
	v_mfma_f32_32x32x16_bf16 v[34:49], v[176:179], v[152:155], v[34:49]
	ds_read_b64_tr_b16 v[172:173], v252 offset:17536
	ds_read_b64_tr_b16 v[174:175], v252 offset:20096
	v_add_f32_e32 v237, v103, v237
	v_exp_f32_e32 v105, v105
	v_add_f32_e32 v237, v104, v237
	v_exp_f32_e32 v106, v106
	s_waitcnt lgkmcnt(10)
	v_mfma_f32_32x32x16_bf16 v[50:65], v[240:243], v[152:155], v[50:65]
	ds_read_b64_tr_b16 v[176:177], v252 offset:17600
	ds_read_b64_tr_b16 v[178:179], v252 offset:20160
	v_add_f32_e32 v237, v105, v237
	v_exp_f32_e32 v107, v107
	v_add_f32_e32 v237, v106, v237
	v_exp_f32_e32 v108, v108
	s_waitcnt lgkmcnt(10)
	v_mfma_f32_32x32x16_bf16 v[34:49], v[244:247], v[156:159], v[34:49]
	ds_read_b64_tr_b16 v[240:241], v252 offset:22656
	ds_read_b64_tr_b16 v[242:243], v252 offset:25216
	v_add_f32_e32 v237, v107, v237
	v_exp_f32_e32 v109, v109
	v_add_f32_e32 v237, v108, v237
	v_exp_f32_e32 v110, v110
	s_waitcnt lgkmcnt(10)
; __device__ __forceinline__ s16x4 vtr(ldsp p) { return __builtin_bit_cast(s16x4, __builtin_amdgcn_ds_read_tr16_b64_v4i16((LAS v4i16_t*)p)); }
; template <bool DIFF>
; __device__ __forceinline__ void attn_unit(const AttnP& A, int b, int h, int qi, ldsp lds) {
;     ...
;             QK_BLOCK();
;             s16x4 vlo[8], vhi[8];
; #pragma unroll
;             for (int t = 0; t < 2; ++t)
; #pragma unroll
;                 for (int j = 0; j < 4; ++j) { vlo[t * 4 + j] = vtr(Vb + trb + (16 * j) * VP + t * 64); vhi[t * 4 + j] = vtr(Vb + trb + (16 * j + 8) * VP + t * 64); }
;             __builtin_amdgcn_sched_barrier(0);
;             MASK_BLOCK();
;             bool full = (kt == kt0);
;             float psa, psb;
;             if (!full) {
;                 EXPSUM_BLOCK();
;                 if (__any(psa + psb > 1.0e18f)) { full = true; QK_BLOCK();
; #pragma unroll
;                     for (int t = 0; t < 2; ++t)
; #pragma unroll
;                         for (int j = 0; j < 4; ++j) { vlo[t * 4 + j] = vtr(Vb + trb + (16 * j) * VP + t * 64); vhi[t * 4 + j] = vtr(Vb + trb + (16 * j + 8) * VP + t * 64); }
;                     MASK_BLOCK(); }
;             }
;             if (full) {
;                 float ma = fmaxf(fmaxf(s0[0], s0[1]), s1[0]), mb = fmaxf(fmaxf(s0[2], s0[3]), s1[1]);
;                 ma = fmaxf(fmaxf(ma, s1[2]), s1[3]);
; #pragma unroll
;                 for (int r = 4; r < 16; r += 4) { ma = fmaxf(fmaxf(ma, s0[r]), s0[r + 1]); mb = fmaxf(fmaxf(mb, s0[r + 2]), s0[r + 3]); ma = fmaxf(fmaxf(ma, s1[r]), s1[r + 1]); mb = fmaxf(fmaxf(mb, s1[r + 2]), s1[r + 3]); }
;                 const float rm = swap32_max(fmaxf(ma, mb));
;                 const float dl = (kt == kt0) ? ((rm == -INFINITY) ? 0.f : rm) : fmaxf(rm, 0.f);
;                 mhat += dl;
; #pragma unroll
;                 for (int r = 0; r < 16; ++r) { s0[r] -= dl; s1[r] -= dl; negm[r] = -mhat; }
;                 const float f = (kt == kt0) ? 1.0f : __builtin_amdgcn_exp2f(-dl);
;                 l_run *= f;
; #pragma unroll
;                 for (int t = 0; t < NTD; ++t)
; #pragma unroll
;                     for (int r = 0; r < 16; ++r) o[t][r] *= f;
;                 EXPSUM_BLOCK();
;             }
;             l_run += psa + psb;
;     ...
;             bf16x8 pw[4];
; #pragma unroll
;             for (int j = 0; j < 4; ++j) {
;                 u32x4 pk;
	v_mfma_f32_32x32x16_bf16 v[50:65], v[248:251], v[156:159], v[50:65]
	ds_read_b64_tr_b16 v[244:245], v252 offset:22720
	ds_read_b64_tr_b16 v[246:247], v252 offset:25280
	v_add_f32_e32 v237, v109, v237
	v_exp_f32_e32 v111, v111
	v_add_f32_e32 v237, v110, v237
	v_exp_f32_e32 v112, v112
	s_waitcnt lgkmcnt(10)
	v_mfma_f32_32x32x16_bf16 v[50:65], v[164:167], v[160:163], v[50:65]
	ds_read_b64_tr_b16 v[248:249], v252 offset:27776
	ds_read_b64_tr_b16 v[250:251], v252 offset:30336
	v_add_f32_e32 v237, v111, v237
	v_exp_f32_e32 v113, v113
	v_add_f32_e32 v237, v112, v237
	s_nop 0
	s_waitcnt lgkmcnt(10)
	v_mfma_f32_32x32x16_bf16 v[34:49], v[168:171], v[160:163], v[34:49]
	ds_read_b64_tr_b16 v[164:165], v252 offset:27840
	ds_read_b64_tr_b16 v[166:167], v252 offset:30400
	v_add_f32_e32 v237, v113, v237
	v_exp_f32_e32 v82, v82
	v_exp_f32_e32 v83, v83
	v_add_f32_e32 v238, 0, v82
	s_waitcnt lgkmcnt(10)
	v_mfma_f32_32x32x16_bf16 v[18:33], v[172:175], v[148:151], v[18:33]
	ds_read_b64_tr_b16 v[168:169], v252 offset:32896
	ds_read_b64_tr_b16 v[170:171], v252 offset:35456
	v_exp_f32_e32 v84, v84
	v_add_f32_e32 v238, v83, v238
	v_exp_f32_e32 v85, v85
	v_add_f32_e32 v238, v84, v238
	s_waitcnt lgkmcnt(10)
	v_mfma_f32_32x32x16_bf16 v[2:17], v[176:179], v[148:151], v[2:17]
	ds_read_b64_tr_b16 v[172:173], v252 offset:32960
	ds_read_b64_tr_b16 v[174:175], v252 offset:35520
	v_exp_f32_e32 v86, v86
	v_add_f32_e32 v238, v85, v238
	v_exp_f32_e32 v87, v87
	v_add_f32_e32 v238, v86, v238
	s_waitcnt lgkmcnt(10)
	v_mfma_f32_32x32x16_bf16 v[18:33], v[240:243], v[152:155], v[18:33]
	v_exp_f32_e32 v88, v88
	v_add_f32_e32 v238, v87, v238
	v_exp_f32_e32 v89, v89
	v_add_f32_e32 v238, v88, v238
	s_waitcnt lgkmcnt(8)
	v_mfma_f32_32x32x16_bf16 v[2:17], v[244:247], v[152:155], v[2:17]
	v_exp_f32_e32 v90, v90
	v_add_f32_e32 v238, v89, v238
	v_exp_f32_e32 v91, v91
	v_add_f32_e32 v238, v90, v238
	s_waitcnt lgkmcnt(6)
	v_mfma_f32_32x32x16_bf16 v[18:33], v[248:251], v[156:159], v[18:33]
	v_exp_f32_e32 v92, v92
	v_add_f32_e32 v238, v91, v238
	v_exp_f32_e32 v93, v93
	v_add_f32_e32 v238, v92, v238
	s_waitcnt lgkmcnt(4)
	v_mfma_f32_32x32x16_bf16 v[2:17], v[164:167], v[156:159], v[2:17]
	v_exp_f32_e32 v94, v94
	v_add_f32_e32 v238, v93, v238
	v_exp_f32_e32 v95, v95
	v_add_f32_e32 v238, v94, v238
	s_waitcnt lgkmcnt(2)
	v_mfma_f32_32x32x16_bf16 v[18:33], v[168:171], v[160:163], v[18:33]
	v_exp_f32_e32 v96, v96
	v_add_f32_e32 v238, v95, v238
	v_exp_f32_e32 v97, v97
	v_add_f32_e32 v238, v96, v238
	s_waitcnt lgkmcnt(0)
	v_mfma_f32_32x32x16_bf16 v[2:17], v[172:175], v[160:163], v[2:17]
	s_nop 0
	v_add_f32_e32 v238, v97, v238
	v_add_f32_e32 v204, v237, v238
	v_cmp_lt_f32_e32 vcc, s85, v204
	s_cbranch_vccnz .Ldc_even_slow
	v_add_f32_e32 v230, v204, v230
	s_waitcnt lgkmcnt(0)
	s_barrier
	s_add_i32 s75, s75, 1
	s_add_i32 s74, s74, 64
	s_cmp_gt_i32 s75, s23
	s_cbranch_scc1 .Ldc_exit
.Ldc_odd:
	ds_read_b128 v[164:167], v234 offset:38144
	ds_read_b128 v[168:171], v234 offset:38176
	ds_read_b128 v[172:175], v234 offset:38208
	ds_read_b128 v[176:179], v234 offset:38240
	ds_read_b128 v[240:243], v234 offset:46848
	ds_read_b128 v[244:247], v234 offset:46880
	v_cvt_pk_bf16_f32 v148, v98, v99
	v_cvt_pk_bf16_f32 v149, v100, v101
	v_cvt_pk_bf16_f32 v150, v102, v103
	v_cvt_pk_bf16_f32 v151, v104, v105
	v_cvt_pk_bf16_f32 v152, v106, v107
	v_cvt_pk_bf16_f32 v153, v108, v109
	v_cvt_pk_bf16_f32 v154, v110, v111
	v_cvt_pk_bf16_f32 v155, v112, v113
	v_cvt_pk_bf16_f32 v156, v82, v83
	v_cvt_pk_bf16_f32 v157, v84, v85
	v_cvt_pk_bf16_f32 v158, v86, v87
	v_cvt_pk_bf16_f32 v159, v88, v89
	v_cvt_pk_bf16_f32 v160, v90, v91
	v_cvt_pk_bf16_f32 v161, v92, v93
	v_cvt_pk_bf16_f32 v162, v94, v95
	v_cvt_pk_bf16_f32 v163, v96, v97
.Ldc_odd_mid:
	s_waitcnt lgkmcnt(5)
	v_mfma_f32_32x32x16_bf16 v[98:113], v[164:167], v[116:119], v[66:81]
	ds_read_b128 v[248:251], v234 offset:46912
	s_waitcnt vmcnt(0)
	s_waitcnt lgkmcnt(5)
	v_mfma_f32_32x32x16_bf16 v[98:113], v[168:171], v[120:123], v[98:113]
	ds_read_b128 v[164:167], v234 offset:46944
	ds_write_b128 v226, v[132:135]
	s_waitcnt lgkmcnt(6)
	v_mfma_f32_32x32x16_bf16 v[98:113], v[172:175], v[124:127], v[98:113]
	ds_read_b64_tr_b16 v[168:169], v231 offset:17472
	ds_read_b64_tr_b16 v[170:171], v231 offset:20032
	ds_write_b128 v228, v[140:143]
	s_waitcnt lgkmcnt(8)
	v_mfma_f32_32x32x16_bf16 v[98:113], v[176:179], v[128:131], v[98:113]
	ds_read_b64_tr_b16 v[172:173], v231 offset:17408
	ds_read_b64_tr_b16 v[174:175], v231 offset:19968
	ds_write_b128 v227, v[136:139] offset:55552
	s_waitcnt lgkmcnt(10)
	v_mfma_f32_32x32x16_bf16 v[82:97], v[240:243], v[116:119], v[66:81]
	ds_read_b64_tr_b16 v[176:177], v231 offset:22592
	ds_read_b64_tr_b16 v[178:179], v231 offset:25152
	ds_write_b128 v229, v[144:147] offset:55552
	s_waitcnt lgkmcnt(12)
	v_mfma_f32_32x32x16_bf16 v[82:97], v[244:247], v[120:123], v[82:97]
	ds_read_b64_tr_b16 v[240:241], v231 offset:22528
	ds_read_b64_tr_b16 v[242:243], v231 offset:25088
	global_load_dwordx4 v[136:139], v[196:197], off offset:2048
	global_load_dwordx4 v[144:147], v[198:199], off offset:2048
	v_lshl_add_u64 v[196:197], v[196:197], 0, s[26:27]
	v_lshl_add_u64 v[198:199], v[198:199], 0, s[26:27]
	s_waitcnt lgkmcnt(13)
	v_mfma_f32_32x32x16_bf16 v[82:97], v[248:251], v[124:127], v[82:97]
	ds_read_b64_tr_b16 v[244:245], v231 offset:27712
	ds_read_b64_tr_b16 v[246:247], v231 offset:30272
	global_load_dwordx4 v[132:135], v[196:197], off offset:1024
	global_load_dwordx4 v[140:143], v[198:199], off offset:1024
	s_waitcnt lgkmcnt(14)
; __device__ __forceinline__ s16x4 vtr(ldsp p) { return __builtin_bit_cast(s16x4, __builtin_amdgcn_ds_read_tr16_b64_v4i16((LAS v4i16_t*)p)); }
; template <bool DIFF>
; __device__ __forceinline__ void attn_unit(const AttnP& A, int b, int h, int qi, ldsp lds) {
;     ...
;             QK_BLOCK();
;             s16x4 vlo[8], vhi[8];
; #pragma unroll
;             for (int t = 0; t < 2; ++t)
; #pragma unroll
;                 for (int j = 0; j < 4; ++j) { vlo[t * 4 + j] = vtr(Vb + trb + (16 * j) * VP + t * 64); vhi[t * 4 + j] = vtr(Vb + trb + (16 * j + 8) * VP + t * 64); }
;             __builtin_amdgcn_sched_barrier(0);
;             MASK_BLOCK();
;             bool full = (kt == kt0);
;             float psa, psb;
;             if (!full) {
;                 EXPSUM_BLOCK();
;                 if (__any(psa + psb > 1.0e18f)) { full = true; QK_BLOCK();
; #pragma unroll
;                     for (int t = 0; t < 2; ++t)
; #pragma unroll
;                         for (int j = 0; j < 4; ++j) { vlo[t * 4 + j] = vtr(Vb + trb + (16 * j) * VP + t * 64); vhi[t * 4 + j] = vtr(Vb + trb + (16 * j + 8) * VP + t * 64); }
;                     MASK_BLOCK(); }
;             }
;             if (full) {
;                 float ma = fmaxf(fmaxf(s0[0], s0[1]), s1[0]), mb = fmaxf(fmaxf(s0[2], s0[3]), s1[1]);
;                 ma = fmaxf(fmaxf(ma, s1[2]), s1[3]);
; #pragma unroll
;                 for (int r = 4; r < 16; r += 4) { ma = fmaxf(fmaxf(ma, s0[r]), s0[r + 1]); mb = fmaxf(fmaxf(mb, s0[r + 2]), s0[r + 3]); ma = fmaxf(fmaxf(ma, s1[r]), s1[r + 1]); mb = fmaxf(fmaxf(mb, s1[r + 2]), s1[r + 3]); }
;                 const float rm = swap32_max(fmaxf(ma, mb));
;                 const float dl = (kt == kt0) ? ((rm == -INFINITY) ? 0.f : rm) : fmaxf(rm, 0.f);
;                 mhat += dl;
; #pragma unroll
;                 for (int r = 0; r < 16; ++r) { s0[r] -= dl; s1[r] -= dl; negm[r] = -mhat; }
;                 const float f = (kt == kt0) ? 1.0f : __builtin_amdgcn_exp2f(-dl);
;                 l_run *= f;
; #pragma unroll
;                 for (int t = 0; t < NTD; ++t)
; #pragma unroll
;                     for (int r = 0; r < 16; ++r) o[t][r] *= f;
;                 EXPSUM_BLOCK();
;             }
;             l_run += psa + psb;
;     ...
;             bf16x8 pw[4];
; #pragma unroll
;             for (int j = 0; j < 4; ++j) {
;                 u32x4 pk;
	v_mfma_f32_32x32x16_bf16 v[82:97], v[164:167], v[128:131], v[82:97]
	ds_read_b64_tr_b16 v[248:249], v231 offset:27648
	ds_read_b64_tr_b16 v[250:251], v231 offset:30208
	v_exp_f32_e32 v98, v98
	v_exp_f32_e32 v99, v99
	v_add_f32_e32 v237, 0, v98
	v_exp_f32_e32 v100, v100
	s_waitcnt lgkmcnt(13)
	v_mfma_f32_32x32x16_bf16 v[34:49], v[168:171], v[148:151], v[34:49]
	ds_read_b64_tr_b16 v[164:165], v231 offset:32768
	ds_read_b64_tr_b16 v[166:167], v231 offset:35328
	v_add_f32_e32 v237, v99, v237
	v_exp_f32_e32 v101, v101
	v_add_f32_e32 v237, v100, v237
	v_exp_f32_e32 v102, v102
	s_waitcnt lgkmcnt(12)
	v_mfma_f32_32x32x16_bf16 v[50:65], v[172:175], v[148:151], v[50:65]
	ds_read_b64_tr_b16 v[168:169], v231 offset:32832
	ds_read_b64_tr_b16 v[170:171], v231 offset:35392
	v_add_f32_e32 v237, v101, v237
	v_exp_f32_e32 v103, v103
	v_add_f32_e32 v237, v102, v237
	v_exp_f32_e32 v104, v104
	s_waitcnt lgkmcnt(11)
	v_mfma_f32_32x32x16_bf16 v[34:49], v[176:179], v[152:155], v[34:49]
	ds_read_b64_tr_b16 v[172:173], v231 offset:17536
	ds_read_b64_tr_b16 v[174:175], v231 offset:20096
	v_add_f32_e32 v237, v103, v237
	v_exp_f32_e32 v105, v105
	v_add_f32_e32 v237, v104, v237
	v_exp_f32_e32 v106, v106
	s_waitcnt lgkmcnt(10)
	v_mfma_f32_32x32x16_bf16 v[50:65], v[240:243], v[152:155], v[50:65]
	ds_read_b64_tr_b16 v[176:177], v231 offset:17600
	ds_read_b64_tr_b16 v[178:179], v231 offset:20160
	v_add_f32_e32 v237, v105, v237
	v_exp_f32_e32 v107, v107
	v_add_f32_e32 v237, v106, v237
	v_exp_f32_e32 v108, v108
	s_waitcnt lgkmcnt(10)
	v_mfma_f32_32x32x16_bf16 v[34:49], v[244:247], v[156:159], v[34:49]
	ds_read_b64_tr_b16 v[240:241], v231 offset:22656
	ds_read_b64_tr_b16 v[242:243], v231 offset:25216
	v_add_f32_e32 v237, v107, v237
	v_exp_f32_e32 v109, v109
	v_add_f32_e32 v237, v108, v237
	v_exp_f32_e32 v110, v110
	s_waitcnt lgkmcnt(10)
	v_mfma_f32_32x32x16_bf16 v[50:65], v[248:251], v[156:159], v[50:65]
	ds_read_b64_tr_b16 v[244:245], v231 offset:22720
	ds_read_b64_tr_b16 v[246:247], v231 offset:25280
	v_add_f32_e32 v237, v109, v237
	v_exp_f32_e32 v111, v111
	v_add_f32_e32 v237, v110, v237
	v_exp_f32_e32 v112, v112
	s_waitcnt lgkmcnt(10)
	v_mfma_f32_32x32x16_bf16 v[50:65], v[164:167], v[160:163], v[50:65]
	ds_read_b64_tr_b16 v[248:249], v231 offset:27776
	ds_read_b64_tr_b16 v[250:251], v231 offset:30336
	v_add_f32_e32 v237, v111, v237
	v_exp_f32_e32 v113, v113
	v_add_f32_e32 v237, v112, v237
	s_nop 0
	s_waitcnt lgkmcnt(10)
	v_mfma_f32_32x32x16_bf16 v[34:49], v[168:171], v[160:163], v[34:49]
	ds_read_b64_tr_b16 v[164:165], v231 offset:27840
	ds_read_b64_tr_b16 v[166:167], v231 offset:30400
	v_add_f32_e32 v237, v113, v237
	v_exp_f32_e32 v82, v82
	v_exp_f32_e32 v83, v83
	v_add_f32_e32 v238, 0, v82
	s_waitcnt lgkmcnt(10)
	v_mfma_f32_32x32x16_bf16 v[18:33], v[172:175], v[148:151], v[18:33]
	ds_read_b64_tr_b16 v[168:169], v231 offset:32896
	ds_read_b64_tr_b16 v[170:171], v231 offset:35456
	v_exp_f32_e32 v84, v84
	v_add_f32_e32 v238, v83, v238
	v_exp_f32_e32 v85, v85
	v_add_f32_e32 v238, v84, v238
	s_waitcnt lgkmcnt(10)
	v_mfma_f32_32x32x16_bf16 v[2:17], v[176:179], v[148:151], v[2:17]
	ds_read_b64_tr_b16 v[172:173], v231 offset:32960
	ds_read_b64_tr_b16 v[174:175], v231 offset:35520
	v_exp_f32_e32 v86, v86
	v_add_f32_e32 v238, v85, v238
	v_exp_f32_e32 v87, v87
	v_add_f32_e32 v238, v86, v238
	s_waitcnt lgkmcnt(10)
	v_mfma_f32_32x32x16_bf16 v[18:33], v[240:243], v[152:155], v[18:33]
	v_exp_f32_e32 v88, v88
	v_add_f32_e32 v238, v87, v238
	v_exp_f32_e32 v89, v89
	v_add_f32_e32 v238, v88, v238
	s_waitcnt lgkmcnt(8)
	v_mfma_f32_32x32x16_bf16 v[2:17], v[244:247], v[152:155], v[2:17]
	v_exp_f32_e32 v90, v90
	v_add_f32_e32 v238, v89, v238
	v_exp_f32_e32 v91, v91
	v_add_f32_e32 v238, v90, v238
	s_waitcnt lgkmcnt(6)
	v_mfma_f32_32x32x16_bf16 v[18:33], v[248:251], v[156:159], v[18:33]
	v_exp_f32_e32 v92, v92
	v_add_f32_e32 v238, v91, v238
	v_exp_f32_e32 v93, v93
	v_add_f32_e32 v238, v92, v238
	s_waitcnt lgkmcnt(4)
	v_mfma_f32_32x32x16_bf16 v[2:17], v[164:167], v[156:159], v[2:17]
	v_exp_f32_e32 v94, v94
	v_add_f32_e32 v238, v93, v238
	v_exp_f32_e32 v95, v95
	v_add_f32_e32 v238, v94, v238
	s_waitcnt lgkmcnt(2)
	v_mfma_f32_32x32x16_bf16 v[18:33], v[168:171], v[160:163], v[18:33]
	v_exp_f32_e32 v96, v96
	v_add_f32_e32 v238, v95, v238
	v_exp_f32_e32 v97, v97
	v_add_f32_e32 v238, v96, v238
	s_waitcnt lgkmcnt(0)
	v_mfma_f32_32x32x16_bf16 v[2:17], v[172:175], v[160:163], v[2:17]
	s_nop 0
	v_add_f32_e32 v238, v97, v238
	v_add_f32_e32 v204, v237, v238
	v_cmp_lt_f32_e32 vcc, s85, v204
	s_cbranch_vccnz .Ldc_odd_slow
	v_add_f32_e32 v230, v204, v230
	s_waitcnt lgkmcnt(0)
	s_barrier
	s_add_i32 s75, s75, 1
	s_add_i32 s74, s74, 64
	s_cmp_le_i32 s75, s23
	s_cbranch_scc1 .Ldc_even
.Ldc_exit:
	v_cvt_pk_bf16_f32 v98, v98, v99
	v_cvt_pk_bf16_f32 v99, v100, v101
	v_cvt_pk_bf16_f32 v100, v102, v103
	v_cvt_pk_bf16_f32 v101, v104, v105
	v_cvt_pk_bf16_f32 v102, v106, v107
	v_cvt_pk_bf16_f32 v103, v108, v109
	v_cvt_pk_bf16_f32 v104, v110, v111
	v_cvt_pk_bf16_f32 v105, v112, v113
	v_cvt_pk_bf16_f32 v82, v82, v83
	v_cvt_pk_bf16_f32 v83, v84, v85
	v_cvt_pk_bf16_f32 v84, v86, v87
	v_cvt_pk_bf16_f32 v85, v88, v89
	v_cvt_pk_bf16_f32 v86, v90, v91
	v_cvt_pk_bf16_f32 v87, v92, v93
	v_cvt_pk_bf16_f32 v88, v94, v95
	v_cvt_pk_bf16_f32 v89, v96, v97

; __device__ __forceinline__ s16x4 vtr(ldsp p) { return __builtin_bit_cast(s16x4, __builtin_amdgcn_ds_read_tr16_b64_v4i16((LAS v4i16_t*)p)); }
; #define MASK_BLOCK() do { if (kt == 0 || kt >= diag0) { \
;             _Pragma("unroll") for (int r = 0; r < 16; ++r) { const int kpp = 64 * kt + crow(r, hi); \
;                 if (kpp < 48 || kpp > q_pp) s0[r] = -INFINITY; \
;                 if (kpp + 32 < 48 || kpp + 32 > q_pp) s1[r] = -INFINITY; } } } while (0)
; template <bool DIFF>
; __device__ __forceinline__ void attn_unit(const AttnP& A, int b, int h, int qi, ldsp lds) {
;     ...
;                 if (__any(psa + psb > 1.0e18f)) { full = true; QK_BLOCK();
; #pragma unroll
;                     for (int t = 0; t < 2; ++t)
; #pragma unroll
;                         for (int j = 0; j < 4; ++j) { vlo[t * 4 + j] = vtr(Vb + trb + (16 * j) * VP + t * 64); vhi[t * 4 + j] = vtr(Vb + trb + (16 * j + 8) * VP + t * 64); }
;                     MASK_BLOCK(); }
;             }
.Ldc_even_slow:
	s_waitcnt lgkmcnt(0)
	ds_read_b128 v[164:167], v234
	ds_read_b128 v[168:171], v234 offset:32
	ds_read_b128 v[172:175], v234 offset:64
	ds_read_b128 v[176:179], v234 offset:96
	ds_read_b128 v[240:243], v234 offset:8704
	ds_read_b128 v[244:247], v234 offset:8736
	ds_read_b128 v[248:251], v234 offset:8768
	ds_read_b128 v[148:151], v234 offset:8800
	s_waitcnt lgkmcnt(0)
	v_mfma_f32_32x32x16_bf16 v[98:113], v[164:167], v[116:119], v[66:81]
	v_mfma_f32_32x32x16_bf16 v[98:113], v[168:171], v[120:123], v[98:113]
	v_mfma_f32_32x32x16_bf16 v[98:113], v[172:175], v[124:127], v[98:113]
	v_mfma_f32_32x32x16_bf16 v[98:113], v[176:179], v[128:131], v[98:113]
	v_mfma_f32_32x32x16_bf16 v[82:97], v[240:243], v[116:119], v[66:81]
	v_mfma_f32_32x32x16_bf16 v[82:97], v[244:247], v[120:123], v[82:97]
	v_mfma_f32_32x32x16_bf16 v[82:97], v[248:251], v[124:127], v[82:97]
	v_mfma_f32_32x32x16_bf16 v[82:97], v[148:151], v[128:131], v[82:97]
	s_nop 7
	s_nop 7
	s_mov_b64 s[48:49], -1
	s_branch .Lda5_full
.Ldc_odd_slow:
	s_waitcnt lgkmcnt(0)
	ds_read_b128 v[164:167], v234 offset:38144
	ds_read_b128 v[168:171], v234 offset:38176
	ds_read_b128 v[172:175], v234 offset:38208
	ds_read_b128 v[176:179], v234 offset:38240
	ds_read_b128 v[240:243], v234 offset:46848
	ds_read_b128 v[244:247], v234 offset:46880
	ds_read_b128 v[248:251], v234 offset:46912
	ds_read_b128 v[148:151], v234 offset:46944
	s_waitcnt lgkmcnt(0)
	v_mfma_f32_32x32x16_bf16 v[98:113], v[164:167], v[116:119], v[66:81]
	v_mfma_f32_32x32x16_bf16 v[98:113], v[168:171], v[120:123], v[98:113]
	v_mfma_f32_32x32x16_bf16 v[98:113], v[172:175], v[124:127], v[98:113]
	v_mfma_f32_32x32x16_bf16 v[98:113], v[176:179], v[128:131], v[98:113]
	v_mfma_f32_32x32x16_bf16 v[82:97], v[240:243], v[116:119], v[66:81]
	v_mfma_f32_32x32x16_bf16 v[82:97], v[244:247], v[120:123], v[82:97]
	v_mfma_f32_32x32x16_bf16 v[82:97], v[248:251], v[124:127], v[82:97]
	v_mfma_f32_32x32x16_bf16 v[82:97], v[148:151], v[128:131], v[82:97]
	s_nop 7
	s_nop 7
	s_mov_b64 s[48:49], -1
	s_branch .Lda5_full
.Ldb_top:
	s_and_b64 vcc, exec, s[16:17]
	s_cbranch_vccz .Ldb_gen
	s_cmp_lt_i32 s75, 2
	s_cbranch_scc1 .Ldb_gen
	s_add_i32 s23, s31, -3
	s_cmp_gt_i32 s75, s23
	s_cbranch_scc1 .Ldb_gen
	v_exp_f32_e32 v148, v98
	v_exp_f32_e32 v164, v82
	v_exp_f32_e32 v149, v99
	v_exp_f32_e32 v165, v83
	v_add_f32_e32 v237, 0, v148
	v_add_f32_e32 v238, 0, v164
	v_exp_f32_e32 v150, v100
	v_exp_f32_e32 v166, v84
	v_add_f32_e32 v237, v149, v237
	v_add_f32_e32 v238, v165, v238
	v_exp_f32_e32 v151, v101
	v_exp_f32_e32 v167, v85
	v_add_f32_e32 v237, v150, v237
	v_add_f32_e32 v238, v166, v238
	v_exp_f32_e32 v152, v102
	v_exp_f32_e32 v168, v86
	v_add_f32_e32 v237, v151, v237
	v_add_f32_e32 v238, v167, v238
	v_exp_f32_e32 v153, v103
	v_exp_f32_e32 v169, v87
	v_add_f32_e32 v237, v152, v237
	v_add_f32_e32 v238, v168, v238
	v_exp_f32_e32 v154, v104
	v_exp_f32_e32 v170, v88
	v_add_f32_e32 v237, v153, v237
	v_add_f32_e32 v238, v169, v238
	v_exp_f32_e32 v155, v105
	v_exp_f32_e32 v171, v89
	v_add_f32_e32 v237, v154, v237
	v_add_f32_e32 v238, v170, v238
	v_exp_f32_e32 v156, v106
	v_exp_f32_e32 v172, v90
	v_add_f32_e32 v237, v155, v237
	v_add_f32_e32 v238, v171, v238
	v_exp_f32_e32 v157, v107
	v_exp_f32_e32 v173, v91
	v_add_f32_e32 v237, v156, v237
	v_add_f32_e32 v238, v172, v238
	v_exp_f32_e32 v158, v108
	v_exp_f32_e32 v174, v92
	v_add_f32_e32 v237, v157, v237
	v_add_f32_e32 v238, v173, v238
	v_exp_f32_e32 v159, v109
	v_exp_f32_e32 v175, v93
	v_add_f32_e32 v237, v158, v237
	v_add_f32_e32 v238, v174, v238
	v_exp_f32_e32 v160, v110
	v_exp_f32_e32 v176, v94
	v_add_f32_e32 v237, v159, v237
	v_add_f32_e32 v238, v175, v238
	v_exp_f32_e32 v161, v111
	v_exp_f32_e32 v177, v95
	v_add_f32_e32 v237, v160, v237
	v_add_f32_e32 v238, v176, v238
	v_exp_f32_e32 v162, v112
	v_exp_f32_e32 v178, v96
	v_add_f32_e32 v237, v161, v237
	v_add_f32_e32 v238, v177, v238
	v_exp_f32_e32 v163, v113
	v_exp_f32_e32 v179, v97
	v_add_f32_e32 v237, v162, v237
	v_add_f32_e32 v238, v178, v238
	s_nop 0
	v_add_f32_e32 v237, v163, v237
	v_add_f32_e32 v238, v179, v238
	v_add_f32_e32 v204, v237, v238
	v_cmp_lt_f32_e32 vcc, s85, v204
	s_cbranch_vccnz .Ldb_s_slow
	v_cvt_pk_bf16_f32 v98, v148, v149
	v_cvt_pk_bf16_f32 v99, v150, v151
	v_cvt_pk_bf16_f32 v100, v152, v153
	v_cvt_pk_bf16_f32 v101, v154, v155
	v_cvt_pk_bf16_f32 v102, v156, v157
	v_cvt_pk_bf16_f32 v103, v158, v159
	v_cvt_pk_bf16_f32 v104, v160, v161
	v_cvt_pk_bf16_f32 v105, v162, v163
	v_cvt_pk_bf16_f32 v82, v164, v165
	v_cvt_pk_bf16_f32 v83, v166, v167
	v_cvt_pk_bf16_f32 v84, v168, v169
	v_cvt_pk_bf16_f32 v85, v170, v171
	v_cvt_pk_bf16_f32 v86, v172, v173
	v_cvt_pk_bf16_f32 v87, v174, v175
	v_cvt_pk_bf16_f32 v88, v176, v177
	v_cvt_pk_bf16_f32 v89, v178, v179
	v_add_f32_e32 v230, v204, v230
	s_branch .Ldc_entry
